# attention epilogue: permlane32_swap pairs + 8 dwordx4 stores instead of 16 dwordx2 per lane
# baseline (speedup 1.0000x reference)
; __device__ __forceinline__ unsigned cvt_pk_bf16(float lo, float hi) { const f32x2 v = {lo, hi}; return __builtin_bit_cast(unsigned, __builtin_convertvector(v, bf16x2_t)); }
; __device__ __forceinline__ float xhalf_sum(float m) { auto rr = __builtin_amdgcn_permlane32_swap(__float_as_uint(m), __float_as_uint(m), false, false); return __uint_as_float(rr[0]) + __uint_as_float(rr[1]); }
; __device__ __forceinline__ void attn_unit2(LAS unsigned char* lds, const bf16_t* __restrict__ Q, const bf16_t* __restrict__ KN, const bf16_t* __restrict__ KPE, ...
;     ...
;     const float inva = __builtin_amdgcn_rcpf(xhalf_sum(la)), invb = __builtin_amdgcn_rcpf(xhalf_sum(lb));
;     bf16_t* op = MIX + (size_t)(qrow0 + wid * 64 + r32) * DM + h * 64 + 4 * hi;
; #pragma unroll
;     for (int g = 0; g < 4; ++g) {
;         u32x2 w0, w1;
;         w0.x = cvt_pk_bf16(oa0[4 * g] * inva, oa0[4 * g + 1] * inva); w0.y = cvt_pk_bf16(oa0[4 * g + 2] * inva, oa0[4 * g + 3] * inva);
;         w1.x = cvt_pk_bf16(oa1[4 * g] * inva, oa1[4 * g + 1] * inva); w1.y = cvt_pk_bf16(oa1[4 * g + 2] * inva, oa1[4 * g + 3] * inva);
;         *(u32x2*)(op + 8 * g) = w0; *(u32x2*)(op + 32 + 8 * g) = w1;
;         w0.x = cvt_pk_bf16(ob0[4 * g] * invb, ob0[4 * g + 1] * invb); w0.y = cvt_pk_bf16(ob0[4 * g + 2] * invb, ob0[4 * g + 3] * invb);
;         w1.x = cvt_pk_bf16(ob1[4 * g] * invb, ob1[4 * g + 1] * invb); w1.y = cvt_pk_bf16(ob1[4 * g + 2] * invb, ob1[4 * g + 3] * invb);
;         *(u32x2*)(op + (size_t)32 * DM + 8 * g) = w0; *(u32x2*)(op + (size_t)32 * DM + 32 + 8 * g) = w1;
;     }
.LBB0_370:
	v_mov_b32_e32 v64, v191
	s_nop 1
	v_permlane32_swap_b32_e32 v191, v64
	v_add_f32_e32 v64, v191, v64
	v_mov_b32_e32 v65, v193
	v_rcp_f32_e32 v64, v64
	s_nop 0
	v_permlane32_swap_b32_e32 v193, v65
	v_add_f32_e32 v65, v193, v65
	v_rcp_f32_e32 v66, v65
	v_readlane_b32 s4, v255, 31
	v_lshlrev_b64 v[68:69], 11, v[178:179]
	v_readlane_b32 s5, v255, 32
	s_lshl_b32 s52, s18, 1
	v_lshl_add_u64 v[68:69], s[4:5], 0, v[68:69]
	v_lshl_add_u64 v[68:69], v[68:69], 0, s[52:53]
	v_lshlrev_b32_e32 v128, 3, v192
	v_lshl_add_u64 v[68:69], v[68:69], 0, v[128:129]
	v_lshl_add_u64 v[68:69], v[68:69], 0, v[128:129]
	v_add_co_u32_e32 v70, vcc, s36, v68
	s_nop 1
	v_addc_co_u32_e32 v71, vcc, 0, v69, vcc
	v_pk_mul_f32 v[16:17], v[16:17], v[64:65] op_sel_hi:[1,0]
	v_pk_mul_f32 v[18:19], v[18:19], v[64:65] op_sel_hi:[1,0]
	v_pk_mul_f32 v[20:21], v[20:21], v[64:65] op_sel_hi:[1,0]
	v_pk_mul_f32 v[22:23], v[22:23], v[64:65] op_sel_hi:[1,0]
	v_cvt_pk_bf16_f32 v72, v16, v17
	v_cvt_pk_bf16_f32 v73, v18, v19
	v_cvt_pk_bf16_f32 v74, v20, v21
	v_cvt_pk_bf16_f32 v75, v22, v23
	s_nop 1
	v_permlane32_swap_b32_e32 v72, v74
	v_permlane32_swap_b32_e32 v73, v75
	global_store_dwordx4 v[68:69], v[72:75], off
	v_pk_mul_f32 v[24:25], v[24:25], v[64:65] op_sel_hi:[1,0]
	v_pk_mul_f32 v[26:27], v[26:27], v[64:65] op_sel_hi:[1,0]
	v_pk_mul_f32 v[28:29], v[28:29], v[64:65] op_sel_hi:[1,0]
	v_pk_mul_f32 v[30:31], v[30:31], v[64:65] op_sel_hi:[1,0]
	v_cvt_pk_bf16_f32 v76, v24, v25
	v_cvt_pk_bf16_f32 v77, v26, v27
	v_cvt_pk_bf16_f32 v78, v28, v29
	v_cvt_pk_bf16_f32 v79, v30, v31
	s_nop 1
	v_permlane32_swap_b32_e32 v76, v78
	v_permlane32_swap_b32_e32 v77, v79
	global_store_dwordx4 v[68:69], v[76:79], off offset:32
	v_pk_mul_f32 v[48:49], v[48:49], v[64:65] op_sel_hi:[1,0]
	v_pk_mul_f32 v[50:51], v[50:51], v[64:65] op_sel_hi:[1,0]
	v_pk_mul_f32 v[52:53], v[52:53], v[64:65] op_sel_hi:[1,0]
	v_pk_mul_f32 v[54:55], v[54:55], v[64:65] op_sel_hi:[1,0]
	v_cvt_pk_bf16_f32 v80, v48, v49
	v_cvt_pk_bf16_f32 v81, v50, v51
	v_cvt_pk_bf16_f32 v82, v52, v53
	v_cvt_pk_bf16_f32 v83, v54, v55
	s_nop 1
	v_permlane32_swap_b32_e32 v80, v82
	v_permlane32_swap_b32_e32 v81, v83
	global_store_dwordx4 v[68:69], v[80:83], off offset:64
	v_pk_mul_f32 v[56:57], v[56:57], v[64:65] op_sel_hi:[1,0]
	v_pk_mul_f32 v[58:59], v[58:59], v[64:65] op_sel_hi:[1,0]
	v_pk_mul_f32 v[60:61], v[60:61], v[64:65] op_sel_hi:[1,0]
	v_pk_mul_f32 v[62:63], v[62:63], v[64:65] op_sel_hi:[1,0]
	v_cvt_pk_bf16_f32 v84, v56, v57
	v_cvt_pk_bf16_f32 v85, v58, v59
	v_cvt_pk_bf16_f32 v86, v60, v61
	v_cvt_pk_bf16_f32 v87, v62, v63
	s_nop 1
	v_permlane32_swap_b32_e32 v84, v86
	v_permlane32_swap_b32_e32 v85, v87
	global_store_dwordx4 v[68:69], v[84:87], off offset:96
	v_pk_mul_f32 v[32:33], v[32:33], v[66:67] op_sel_hi:[1,0]
	v_pk_mul_f32 v[34:35], v[34:35], v[66:67] op_sel_hi:[1,0]
	v_pk_mul_f32 v[36:37], v[36:37], v[66:67] op_sel_hi:[1,0]
	v_pk_mul_f32 v[38:39], v[38:39], v[66:67] op_sel_hi:[1,0]
	v_cvt_pk_bf16_f32 v72, v32, v33
	v_cvt_pk_bf16_f32 v73, v34, v35
	v_cvt_pk_bf16_f32 v74, v36, v37
	v_cvt_pk_bf16_f32 v75, v38, v39
	s_nop 1
	v_permlane32_swap_b32_e32 v72, v74
	v_permlane32_swap_b32_e32 v73, v75
	global_store_dwordx4 v[70:71], v[72:75], off
	v_pk_mul_f32 v[40:41], v[40:41], v[66:67] op_sel_hi:[1,0]
	v_pk_mul_f32 v[42:43], v[42:43], v[66:67] op_sel_hi:[1,0]
	v_pk_mul_f32 v[44:45], v[44:45], v[66:67] op_sel_hi:[1,0]
	v_pk_mul_f32 v[46:47], v[46:47], v[66:67] op_sel_hi:[1,0]
	v_cvt_pk_bf16_f32 v76, v40, v41
	v_cvt_pk_bf16_f32 v77, v42, v43
	v_cvt_pk_bf16_f32 v78, v44, v45
	v_cvt_pk_bf16_f32 v79, v46, v47
	s_nop 1
	v_permlane32_swap_b32_e32 v76, v78
	v_permlane32_swap_b32_e32 v77, v79
	global_store_dwordx4 v[70:71], v[76:79], off offset:32
	v_pk_mul_f32 v[0:1], v[0:1], v[66:67] op_sel_hi:[1,0]
	v_pk_mul_f32 v[2:3], v[2:3], v[66:67] op_sel_hi:[1,0]
	v_pk_mul_f32 v[4:5], v[4:5], v[66:67] op_sel_hi:[1,0]
	v_pk_mul_f32 v[6:7], v[6:7], v[66:67] op_sel_hi:[1,0]
	v_cvt_pk_bf16_f32 v80, v0, v1
	v_cvt_pk_bf16_f32 v81, v2, v3
	v_cvt_pk_bf16_f32 v82, v4, v5
	v_cvt_pk_bf16_f32 v83, v6, v7
	s_nop 1
	v_permlane32_swap_b32_e32 v80, v82
	v_permlane32_swap_b32_e32 v81, v83
	global_store_dwordx4 v[70:71], v[80:83], off offset:64
	v_pk_mul_f32 v[8:9], v[8:9], v[66:67] op_sel_hi:[1,0]
	v_pk_mul_f32 v[10:11], v[10:11], v[66:67] op_sel_hi:[1,0]
	v_pk_mul_f32 v[12:13], v[12:13], v[66:67] op_sel_hi:[1,0]
	v_pk_mul_f32 v[14:15], v[14:15], v[66:67] op_sel_hi:[1,0]
	v_cvt_pk_bf16_f32 v84, v8, v9
	v_cvt_pk_bf16_f32 v85, v10, v11
	v_cvt_pk_bf16_f32 v86, v12, v13
	v_cvt_pk_bf16_f32 v87, v14, v15
	s_nop 1
	v_permlane32_swap_b32_e32 v84, v86
	v_permlane32_swap_b32_e32 v85, v87
	global_store_dwordx4 v[70:71], v[84:87], off offset:96
	s_mov_b64 s[16:17], s[38:39]
